# v23 + QK-norm row reductions via v_permlane16_swap / v_permlane32_swap instead of two ds_bpermute round trips per row block
# speedup vs baseline: 1.0100x; 1.0100x over previous
; __device__ __forceinline__ u32x4 pack8(const f32x4& a, const f32x4& b) { u32x4 w; w.x = pk2(a[0], a[1]); w.y = pk2(a[2], a[3]); w.z = pk2(b[0], b[1]); w.w = pk2(b[2], b[3]); return w; }
;     __device__ __forceinline__ void operator()(const AccT& acc, const Unit& u, int wr, int wc, int fr, int fq) const {
;     ...
;                 const int row = row0 + ai * 128 + m * 16; float rs = 1.f;
;                 if (kind < 2) { float ss = 0.f;
; #pragma unroll
;                     for (int bj = 0; bj < 2; ++bj)
; #pragma unroll
;                         for (int n = 0; n < 2; ++n) { const f32x4 v = acc[ai][bj][m][n]; ss += (v[0] * v[0] + v[1] * v[1]) + (v[2] * v[2] + v[3] * v[3]); }
;                     ss += __shfl_xor(ss, 16); ss += __shfl_xor(ss, 32); rs = rsqrtf(ss * (1.f / 64.f) + EPS); }
;                 bf16_t* rp = base + (size_t)row * BR + tile * 256 + 64 * wc + 8 * fq;
; #pragma unroll
;                 for (int bj = 0; bj < 2; ++bj) { const f32x4 v0 = acc[ai][bj][m][0] * rs * gv[bj][0], v1 = acc[ai][bj][m][1] * rs * gv[bj][1];
;                     __builtin_nontemporal_store(pack8(v0, v1), (u32x4*)(rp + 32 * bj)); }
.Lqk_nog:
	s_andn2_b64 s[6:7], exec, s[70:71]
	v_mov_b32_e32 v168, 1.0
	s_and_b64 vcc, exec, s[6:7]
	v_mov_b32_e32 v170, 1.0
	s_cbranch_vccnz .LBB0_129
	v_pk_mul_f32 v[164:165], v[126:127], v[126:127]
	v_pk_mul_f32 v[166:167], v[124:125], v[124:125]
	v_mul_f32_e32 v170, v112, v112
	v_pk_mov_b32 v[180:181], v[166:167], v[164:165] op_sel:[1,0]
	v_mov_b32_e32 v167, v165
	v_pk_add_f32 v[164:165], v[180:181], v[166:167]
	v_pk_mul_f32 v[166:167], v[122:123], v[122:123]
	v_pk_mul_f32 v[180:181], v[120:121], v[120:121]
	v_pk_add_f32 v[164:165], v[164:165], v[164:165] op_sel:[0,1] op_sel_hi:[1,0]
	v_pk_mov_b32 v[182:183], v[180:181], v[166:167] op_sel:[1,0]
	v_mov_b32_e32 v181, v167
	v_pk_add_f32 v[166:167], v[182:183], v[180:181]
	v_mul_f32_e32 v180, v113, v113
	v_pk_add_f32 v[166:167], v[166:167], v[166:167] op_sel:[0,1] op_sel_hi:[1,0]
	v_mov_b32_e32 v165, v170
	v_mov_b32_e32 v167, v180
	v_pk_add_f32 v[164:165], v[164:165], v[166:167]
	v_mul_f32_e32 v166, v117, v117
	v_mul_f32_e32 v181, v114, v114
	v_pk_fma_f32 v[166:167], v[116:117], v[116:117], v[166:167] op_sel_hi:[1,1,0]
	v_mul_f32_e32 v170, v119, v119
	v_mul_f32_e32 v182, v115, v115
	v_mov_b32_e32 v167, v181
	v_pk_fma_f32 v[180:181], v[118:119], v[118:119], v[170:171] op_sel_hi:[1,1,0]
	s_nop 0
	v_mov_b32_e32 v181, v182
	v_pk_add_f32 v[166:167], v[166:167], v[180:181]
	s_nop 0
	v_pk_add_f32 v[164:165], v[164:165], v[166:167]
	s_nop 0
	v_add_f32_e32 v164, v164, v165
	v_mov_b32_e32 v165, v164
	s_nop 1
	v_permlane16_swap_b32_e32 v165, v164
	v_add_f32_e32 v164, v164, v165
	v_mov_b32_e32 v165, v164
	s_nop 1
	v_permlane32_swap_b32_e32 v165, v164
	v_add_f32_e32 v164, v164, v165
	v_fmamk_f32 v164, v164, 0x3c800000, v178
	v_mul_f32_e32 v165, 0x4b800000, v164
	v_cmp_gt_f32_e32 vcc, s81, v164
	s_nop 1
	v_cndmask_b32_e32 v164, v164, v165, vcc
	v_rsq_f32_e32 v164, v164
	s_nop 0
	v_mul_f32_e32 v165, 0x45800000, v164
	v_cndmask_b32_e32 v170, v164, v165, vcc
.LBB0_129:
	s_ashr_i32 s67, s66, 31
	s_lshl_b64 s[70:71], s[66:67], 27
	s_add_u32 s43, s34, s70
	s_addc_u32 s53, s35, s71
	s_cmp_eq_u32 s66, 2
	s_cselect_b32 s53, s29, s53
	s_cselect_b32 s43, s28, s43
	v_lshl_add_u32 v164, s62, 8, v139
	s_lshl_b32 s62, s64, 9
	s_and_b32 s62, s62, 0xe00
	s_add_u32 s43, s43, s62
	s_addc_u32 s53, s53, 0
	s_add_u32 s66, s43, s82
	s_addc_u32 s67, s53, 0
	v_lshlrev_b32_e32 v166, 1, v138
	v_mov_b32_e32 v167, v137
	v_ashrrev_i32_e32 v165, 31, v164
	v_lshl_add_u64 v[166:167], s[66:67], 0, v[166:167]
	v_lshlrev_b64 v[180:181], 12, v[164:165]
	v_pk_mul_f32 v[126:127], v[126:127], v[170:171] op_sel_hi:[1,0]
	v_pk_mul_f32 v[124:125], v[124:125], v[170:171] op_sel_hi:[1,0]
	v_pk_mul_f32 v[122:123], v[122:123], v[170:171] op_sel_hi:[1,0]
	v_pk_mul_f32 v[120:121], v[120:121], v[170:171] op_sel_hi:[1,0]
	v_lshl_add_u64 v[180:181], v[166:167], 0, v[180:181]
	v_pk_mul_f32 v[126:127], v[152:153], v[126:127]
	v_pk_mul_f32 v[124:125], v[150:151], v[124:125]
	v_pk_mul_f32 v[182:183], v[156:157], v[122:123]
	v_pk_mul_f32 v[122:123], v[148:149], v[120:121]
	v_cvt_pk_bf16_f32 v120, v124, v125
	v_cvt_pk_bf16_f32 v121, v126, v127
	v_pk_mul_f32 v[114:115], v[114:115], v[170:171] op_sel_hi:[1,0]
	v_pk_mul_f32 v[112:113], v[112:113], v[170:171] op_sel_hi:[1,0]
	v_cvt_pk_bf16_f32 v122, v122, v123
	v_cvt_pk_bf16_f32 v123, v182, v183
	global_store_dwordx4 v[180:181], v[120:123], off nt
	v_pk_mul_f32 v[118:119], v[118:119], v[170:171] op_sel_hi:[1,0]
	v_pk_mul_f32 v[116:117], v[116:117], v[170:171] op_sel_hi:[1,0]
	v_pk_mul_f32 v[120:121], v[162:163], v[114:115]
	v_pk_mul_f32 v[114:115], v[154:155], v[112:113]
	s_and_b64 vcc, exec, s[6:7]
	v_pk_mul_f32 v[118:119], v[160:161], v[118:119]
	v_pk_mul_f32 v[116:117], v[158:159], v[116:117]
	s_nop 0
	v_cvt_pk_bf16_f32 v112, v116, v117
	v_cvt_pk_bf16_f32 v113, v118, v119
	v_cvt_pk_bf16_f32 v114, v114, v115
	v_cvt_pk_bf16_f32 v115, v120, v121
	global_store_dwordx4 v[180:181], v[112:115], off offset:64 nt
	s_cbranch_vccnz .LBB0_131
	s_nop 0
	v_pk_mul_f32 v[112:113], v[110:111], v[110:111]
	v_pk_mul_f32 v[114:115], v[108:109], v[108:109]
	s_nop 0
	v_pk_mov_b32 v[116:117], v[114:115], v[112:113] op_sel:[1,0]
	v_mov_b32_e32 v115, v113
	v_pk_add_f32 v[112:113], v[116:117], v[114:115]
	v_pk_mul_f32 v[114:115], v[106:107], v[106:107]
	v_pk_mul_f32 v[116:117], v[104:105], v[104:105]
	v_pk_add_f32 v[112:113], v[112:113], v[112:113] op_sel:[0,1] op_sel_hi:[1,0]
	v_pk_mov_b32 v[118:119], v[116:117], v[114:115] op_sel:[1,0]
	v_mov_b32_e32 v117, v115
	v_pk_add_f32 v[114:115], v[118:119], v[116:117]
	v_mul_f32_e32 v116, v96, v96
	v_mul_f32_e32 v117, v97, v97
	v_pk_add_f32 v[114:115], v[114:115], v[114:115] op_sel:[0,1] op_sel_hi:[1,0]
	v_mov_b32_e32 v113, v116
	v_mov_b32_e32 v115, v117
	v_pk_add_f32 v[112:113], v[112:113], v[114:115]
	v_mul_f32_e32 v114, v101, v101
	v_mul_f32_e32 v116, v103, v103
	v_mul_f32_e32 v118, v98, v98
	v_mul_f32_e32 v119, v99, v99
	v_pk_fma_f32 v[114:115], v[100:101], v[100:101], v[114:115] op_sel_hi:[1,1,0]
	v_pk_fma_f32 v[116:117], v[102:103], v[102:103], v[116:117] op_sel_hi:[1,1,0]
	v_mov_b32_e32 v115, v118
	v_mov_b32_e32 v117, v119
	v_pk_add_f32 v[114:115], v[114:115], v[116:117]
	s_nop 0
	v_pk_add_f32 v[112:113], v[112:113], v[114:115]
	s_nop 0
	v_add_f32_e32 v112, v112, v113
	v_mov_b32_e32 v113, v112
	s_nop 1
	v_permlane16_swap_b32_e32 v113, v112
	v_add_f32_e32 v112, v112, v113
	v_mov_b32_e32 v113, v112
	s_nop 1
	v_permlane32_swap_b32_e32 v113, v112
	v_add_f32_e32 v112, v112, v113
	v_fmamk_f32 v112, v112, 0x3c800000, v178
	v_mul_f32_e32 v113, 0x4b800000, v112
	v_cmp_gt_f32_e32 vcc, s81, v112
	s_nop 1
	v_cndmask_b32_e32 v112, v112, v113, vcc
	v_rsq_f32_e32 v112, v112
	s_nop 0
	v_mul_f32_e32 v113, 0x45800000, v112
	v_cndmask_b32_e32 v168, v112, v113, vcc
; __device__ __forceinline__ u32x4 pack8(const f32x4& a, const f32x4& b) { u32x4 w; w.x = pk2(a[0], a[1]); w.y = pk2(a[2], a[3]); w.z = pk2(b[0], b[1]); w.w = pk2(b[2], b[3]); return w; }
;     __device__ __forceinline__ void operator()(const AccT& acc, const Unit& u, int wr, int wc, int fr, int fq) const {
;     ...
;                 const int row = row0 + ai * 128 + m * 16; float rs = 1.f;
;                 if (kind < 2) { float ss = 0.f;
; #pragma unroll
;                     for (int bj = 0; bj < 2; ++bj)
; #pragma unroll
;                         for (int n = 0; n < 2; ++n) { const f32x4 v = acc[ai][bj][m][n]; ss += (v[0] * v[0] + v[1] * v[1]) + (v[2] * v[2] + v[3] * v[3]); }
;                     ss += __shfl_xor(ss, 16); ss += __shfl_xor(ss, 32); rs = rsqrtf(ss * (1.f / 64.f) + EPS); }
;                 bf16_t* rp = base + (size_t)row * BR + tile * 256 + 64 * wc + 8 * fq;
; #pragma unroll
;                 for (int bj = 0; bj < 2; ++bj) { const f32x4 v0 = acc[ai][bj][m][0] * rs * gv[bj][0], v1 = acc[ai][bj][m][1] * rs * gv[bj][1];
;                     __builtin_nontemporal_store(pack8(v0, v1), (u32x4*)(rp + 32 * bj)); }
.LBB0_131:
	s_nop 0
	v_or_b32_e32 v112, 16, v164
	v_ashrrev_i32_e32 v113, 31, v112
	v_lshlrev_b64 v[112:113], 12, v[112:113]
	v_pk_mul_f32 v[110:111], v[110:111], v[168:169] op_sel_hi:[1,0]
	v_pk_mul_f32 v[108:109], v[108:109], v[168:169] op_sel_hi:[1,0]
	v_pk_mul_f32 v[106:107], v[106:107], v[168:169] op_sel_hi:[1,0]
	v_pk_mul_f32 v[104:105], v[104:105], v[168:169] op_sel_hi:[1,0]
	v_lshl_add_u64 v[112:113], v[166:167], 0, v[112:113]
	v_pk_mul_f32 v[110:111], v[152:153], v[110:111]
	v_pk_mul_f32 v[108:109], v[150:151], v[108:109]
	v_pk_mul_f32 v[114:115], v[156:157], v[106:107]
	v_pk_mul_f32 v[106:107], v[148:149], v[104:105]
	v_cvt_pk_bf16_f32 v104, v108, v109
	v_cvt_pk_bf16_f32 v105, v110, v111
	v_pk_mul_f32 v[98:99], v[98:99], v[168:169] op_sel_hi:[1,0]
	v_pk_mul_f32 v[96:97], v[96:97], v[168:169] op_sel_hi:[1,0]
	v_cvt_pk_bf16_f32 v106, v106, v107
	v_cvt_pk_bf16_f32 v107, v114, v115
	global_store_dwordx4 v[112:113], v[104:107], off nt
	v_pk_mul_f32 v[102:103], v[102:103], v[168:169] op_sel_hi:[1,0]
	v_pk_mul_f32 v[100:101], v[100:101], v[168:169] op_sel_hi:[1,0]
	v_pk_mul_f32 v[104:105], v[162:163], v[98:99]
	v_pk_mul_f32 v[98:99], v[154:155], v[96:97]
	v_pk_mul_f32 v[102:103], v[160:161], v[102:103]
	v_pk_mul_f32 v[100:101], v[158:159], v[100:101]
	s_and_b64 vcc, exec, s[6:7]
	v_cvt_pk_bf16_f32 v96, v100, v101
	v_cvt_pk_bf16_f32 v97, v102, v103
	v_cvt_pk_bf16_f32 v98, v98, v99
	v_cvt_pk_bf16_f32 v99, v104, v105
	global_store_dwordx4 v[112:113], v[96:99], off offset:64 nt
	s_nop 1
	v_mov_b32_e32 v96, 1.0
	v_mov_b32_e32 v98, 1.0
	s_cbranch_vccnz .LBB0_133
	v_pk_mul_f32 v[98:99], v[94:95], v[94:95]
	v_pk_mul_f32 v[100:101], v[92:93], v[92:93]
	v_mul_f32_e32 v97, v80, v80
	v_pk_mov_b32 v[102:103], v[100:101], v[98:99] op_sel:[1,0]
	v_mov_b32_e32 v101, v99
	v_pk_add_f32 v[98:99], v[102:103], v[100:101]
	v_pk_mul_f32 v[100:101], v[90:91], v[90:91]
	v_pk_mul_f32 v[102:103], v[88:89], v[88:89]
	v_pk_add_f32 v[98:99], v[98:99], v[98:99] op_sel:[0,1] op_sel_hi:[1,0]
	v_pk_mov_b32 v[104:105], v[102:103], v[100:101] op_sel:[1,0]
	v_mov_b32_e32 v103, v101
	v_pk_add_f32 v[100:101], v[104:105], v[102:103]
	v_mul_f32_e32 v102, v81, v81
	v_pk_add_f32 v[100:101], v[100:101], v[100:101] op_sel:[0,1] op_sel_hi:[1,0]
	v_mov_b32_e32 v99, v97
	v_mov_b32_e32 v101, v102
	v_pk_add_f32 v[98:99], v[98:99], v[100:101]
	v_mul_f32_e32 v100, v85, v85
	v_mul_f32_e32 v103, v82, v82
	v_pk_fma_f32 v[100:101], v[84:85], v[84:85], v[100:101] op_sel_hi:[1,1,0]
	v_mul_f32_e32 v102, v87, v87
	v_mul_f32_e32 v104, v83, v83
	v_mov_b32_e32 v101, v103
	v_pk_fma_f32 v[102:103], v[86:87], v[86:87], v[102:103] op_sel_hi:[1,1,0]
	s_nop 0
	v_mov_b32_e32 v103, v104
	v_pk_add_f32 v[100:101], v[100:101], v[102:103]
	s_nop 0
	v_pk_add_f32 v[98:99], v[98:99], v[100:101]
	s_nop 0
	v_add_f32_e32 v97, v98, v99
	v_mov_b32_e32 v98, v97
	s_nop 1
	v_permlane16_swap_b32_e32 v98, v97
	v_add_f32_e32 v97, v97, v98
	v_mov_b32_e32 v98, v97
	s_nop 1
	v_permlane32_swap_b32_e32 v98, v97
	v_add_f32_e32 v97, v97, v98
	v_fmamk_f32 v97, v97, 0x3c800000, v178
	v_mul_f32_e32 v98, 0x4b800000, v97
	v_cmp_gt_f32_e32 vcc, s81, v97
	s_nop 1
	v_cndmask_b32_e32 v97, v97, v98, vcc
	v_rsq_f32_e32 v97, v97
	s_nop 0
	v_mul_f32_e32 v98, 0x45800000, v97
	v_cndmask_b32_e32 v98, v97, v98, vcc
.LBB0_133:
	v_or_b32_e32 v100, 32, v164
	v_ashrrev_i32_e32 v101, 31, v100
	v_lshlrev_b64 v[100:101], 12, v[100:101]
	v_pk_mul_f32 v[94:95], v[94:95], v[98:99] op_sel_hi:[1,0]
	v_pk_mul_f32 v[92:93], v[92:93], v[98:99] op_sel_hi:[1,0]
	v_pk_mul_f32 v[90:91], v[90:91], v[98:99] op_sel_hi:[1,0]
	v_pk_mul_f32 v[88:89], v[88:89], v[98:99] op_sel_hi:[1,0]
	v_lshl_add_u64 v[100:101], v[166:167], 0, v[100:101]
	v_pk_mul_f32 v[94:95], v[152:153], v[94:95]
	v_pk_mul_f32 v[92:93], v[150:151], v[92:93]
	v_pk_mul_f32 v[102:103], v[156:157], v[90:91]
	v_pk_mul_f32 v[90:91], v[148:149], v[88:89]
	v_cvt_pk_bf16_f32 v88, v92, v93
	v_cvt_pk_bf16_f32 v89, v94, v95
	v_pk_mul_f32 v[82:83], v[82:83], v[98:99] op_sel_hi:[1,0]
	v_pk_mul_f32 v[80:81], v[80:81], v[98:99] op_sel_hi:[1,0]
	v_cvt_pk_bf16_f32 v90, v90, v91
	v_cvt_pk_bf16_f32 v91, v102, v103
	global_store_dwordx4 v[100:101], v[88:91], off nt
	v_pk_mul_f32 v[86:87], v[86:87], v[98:99] op_sel_hi:[1,0]
	v_pk_mul_f32 v[84:85], v[84:85], v[98:99] op_sel_hi:[1,0]
	v_pk_mul_f32 v[88:89], v[162:163], v[82:83]
	v_pk_mul_f32 v[82:83], v[154:155], v[80:81]
	s_and_b64 vcc, exec, s[6:7]
	v_pk_mul_f32 v[86:87], v[160:161], v[86:87]
	v_pk_mul_f32 v[84:85], v[158:159], v[84:85]
	s_nop 0
	v_cvt_pk_bf16_f32 v80, v84, v85
	v_cvt_pk_bf16_f32 v81, v86, v87
	v_cvt_pk_bf16_f32 v82, v82, v83
	v_cvt_pk_bf16_f32 v83, v88, v89
	global_store_dwordx4 v[100:101], v[80:83], off offset:64 nt
	s_cbranch_vccnz .LBB0_135
	s_nop 0
	v_pk_mul_f32 v[80:81], v[78:79], v[78:79]
	v_pk_mul_f32 v[82:83], v[76:77], v[76:77]
	s_nop 0
	v_pk_mov_b32 v[84:85], v[82:83], v[80:81] op_sel:[1,0]
	v_mov_b32_e32 v83, v81
	v_pk_add_f32 v[80:81], v[84:85], v[82:83]
	v_pk_mul_f32 v[82:83], v[74:75], v[74:75]
	v_pk_mul_f32 v[84:85], v[72:73], v[72:73]
	v_pk_add_f32 v[80:81], v[80:81], v[80:81] op_sel:[0,1] op_sel_hi:[1,0]
	v_pk_mov_b32 v[86:87], v[84:85], v[82:83] op_sel:[1,0]
	v_mov_b32_e32 v85, v83
	v_pk_add_f32 v[82:83], v[86:87], v[84:85]
	v_mul_f32_e32 v84, v64, v64
	v_mul_f32_e32 v85, v65, v65
	v_pk_add_f32 v[82:83], v[82:83], v[82:83] op_sel:[0,1] op_sel_hi:[1,0]
	v_mov_b32_e32 v81, v84
	v_mov_b32_e32 v83, v85
	v_pk_add_f32 v[80:81], v[80:81], v[82:83]
	v_mul_f32_e32 v82, v69, v69
	v_mul_f32_e32 v84, v71, v71
	v_mul_f32_e32 v86, v66, v66
	v_mul_f32_e32 v87, v67, v67
	v_pk_fma_f32 v[82:83], v[68:69], v[68:69], v[82:83] op_sel_hi:[1,1,0]
	v_pk_fma_f32 v[84:85], v[70:71], v[70:71], v[84:85] op_sel_hi:[1,1,0]
	v_mov_b32_e32 v83, v86
	v_mov_b32_e32 v85, v87
	v_pk_add_f32 v[82:83], v[82:83], v[84:85]
	s_nop 0
	v_pk_add_f32 v[80:81], v[80:81], v[82:83]
	s_nop 0
	v_add_f32_e32 v80, v80, v81
	v_mov_b32_e32 v81, v80
	s_nop 1
	v_permlane16_swap_b32_e32 v81, v80
	v_add_f32_e32 v80, v80, v81
	v_mov_b32_e32 v81, v80
	s_nop 1
	v_permlane32_swap_b32_e32 v81, v80
	v_add_f32_e32 v80, v80, v81
	v_fmamk_f32 v80, v80, 0x3c800000, v178
	v_mul_f32_e32 v81, 0x4b800000, v80
	v_cmp_gt_f32_e32 vcc, s81, v80
	s_nop 1
	v_cndmask_b32_e32 v80, v80, v81, vcc
	v_rsq_f32_e32 v80, v80
	s_nop 0
	v_mul_f32_e32 v81, 0x45800000, v80
	v_cndmask_b32_e32 v96, v80, v81, vcc
; __device__ __forceinline__ u32x4 pack8(const f32x4& a, const f32x4& b) { u32x4 w; w.x = pk2(a[0], a[1]); w.y = pk2(a[2], a[3]); w.z = pk2(b[0], b[1]); w.w = pk2(b[2], b[3]); return w; }
;     __device__ __forceinline__ void operator()(const AccT& acc, const Unit& u, int wr, int wc, int fr, int fq) const {
;     ...
;                 const int row = row0 + ai * 128 + m * 16; float rs = 1.f;
;                 if (kind < 2) { float ss = 0.f;
; #pragma unroll
;                     for (int bj = 0; bj < 2; ++bj)
; #pragma unroll
;                         for (int n = 0; n < 2; ++n) { const f32x4 v = acc[ai][bj][m][n]; ss += (v[0] * v[0] + v[1] * v[1]) + (v[2] * v[2] + v[3] * v[3]); }
;                     ss += __shfl_xor(ss, 16); ss += __shfl_xor(ss, 32); rs = rsqrtf(ss * (1.f / 64.f) + EPS); }
;                 bf16_t* rp = base + (size_t)row * BR + tile * 256 + 64 * wc + 8 * fq;
; #pragma unroll
;                 for (int bj = 0; bj < 2; ++bj) { const f32x4 v0 = acc[ai][bj][m][0] * rs * gv[bj][0], v1 = acc[ai][bj][m][1] * rs * gv[bj][1];
;                     __builtin_nontemporal_store(pack8(v0, v1), (u32x4*)(rp + 32 * bj)); }
.LBB0_135:
	s_nop 0
	v_or_b32_e32 v80, 48, v164
	v_ashrrev_i32_e32 v81, 31, v80
	v_lshlrev_b64 v[80:81], 12, v[80:81]
	v_pk_mul_f32 v[78:79], v[78:79], v[96:97] op_sel_hi:[1,0]
	v_pk_mul_f32 v[76:77], v[76:77], v[96:97] op_sel_hi:[1,0]
	v_pk_mul_f32 v[74:75], v[74:75], v[96:97] op_sel_hi:[1,0]
	v_pk_mul_f32 v[72:73], v[72:73], v[96:97] op_sel_hi:[1,0]
	v_lshl_add_u64 v[80:81], v[166:167], 0, v[80:81]
	v_pk_mul_f32 v[78:79], v[152:153], v[78:79]
	v_pk_mul_f32 v[76:77], v[150:151], v[76:77]
	v_pk_mul_f32 v[82:83], v[156:157], v[74:75]
	v_pk_mul_f32 v[74:75], v[148:149], v[72:73]
	v_cvt_pk_bf16_f32 v72, v76, v77
	v_cvt_pk_bf16_f32 v73, v78, v79
	v_pk_mul_f32 v[68:69], v[68:69], v[96:97] op_sel_hi:[1,0]
	v_pk_mul_f32 v[66:67], v[66:67], v[96:97] op_sel_hi:[1,0]
	v_pk_mul_f32 v[64:65], v[64:65], v[96:97] op_sel_hi:[1,0]
	v_cvt_pk_bf16_f32 v74, v74, v75
	v_cvt_pk_bf16_f32 v75, v82, v83
	global_store_dwordx4 v[80:81], v[72:75], off nt
	v_pk_mul_f32 v[70:71], v[70:71], v[96:97] op_sel_hi:[1,0]
	v_pk_mul_f32 v[68:69], v[158:159], v[68:69]
	v_pk_mul_f32 v[72:73], v[162:163], v[66:67]
	v_pk_mul_f32 v[66:67], v[154:155], v[64:65]
	v_cvt_pk_bf16_f32 v64, v68, v69
	v_pk_mul_f32 v[70:71], v[160:161], v[70:71]
	s_and_b64 vcc, exec, s[6:7]
	v_cvt_pk_bf16_f32 v65, v70, v71
	v_cvt_pk_bf16_f32 v66, v66, v67
	v_cvt_pk_bf16_f32 v67, v72, v73
	global_store_dwordx4 v[80:81], v[64:67], off offset:64 nt
	v_mov_b32_e32 v68, 1.0
	s_nop 0
	v_mov_b32_e32 v64, 1.0
	s_cbranch_vccnz .LBB0_137
	v_pk_mul_f32 v[66:67], v[62:63], v[62:63]
	v_pk_mul_f32 v[68:69], v[60:61], v[60:61]
	v_mul_f32_e32 v65, v48, v48
	v_pk_mov_b32 v[70:71], v[68:69], v[66:67] op_sel:[1,0]
	v_mov_b32_e32 v69, v67
	v_pk_add_f32 v[66:67], v[70:71], v[68:69]
	v_pk_mul_f32 v[68:69], v[58:59], v[58:59]
	v_pk_mul_f32 v[70:71], v[56:57], v[56:57]
	v_pk_add_f32 v[66:67], v[66:67], v[66:67] op_sel:[0,1] op_sel_hi:[1,0]
	v_pk_mov_b32 v[72:73], v[70:71], v[68:69] op_sel:[1,0]
	v_mov_b32_e32 v71, v69
	v_pk_add_f32 v[68:69], v[72:73], v[70:71]
	v_mul_f32_e32 v70, v49, v49
	v_pk_add_f32 v[68:69], v[68:69], v[68:69] op_sel:[0,1] op_sel_hi:[1,0]
	v_mov_b32_e32 v67, v65
	v_mov_b32_e32 v69, v70
	v_pk_add_f32 v[66:67], v[66:67], v[68:69]
	v_mul_f32_e32 v68, v53, v53
	v_mul_f32_e32 v71, v50, v50
	v_pk_fma_f32 v[68:69], v[52:53], v[52:53], v[68:69] op_sel_hi:[1,1,0]
	v_mul_f32_e32 v70, v55, v55
	v_mul_f32_e32 v72, v51, v51
	v_mov_b32_e32 v69, v71
	v_pk_fma_f32 v[70:71], v[54:55], v[54:55], v[70:71] op_sel_hi:[1,1,0]
	s_nop 0
	v_mov_b32_e32 v71, v72
	v_pk_add_f32 v[68:69], v[68:69], v[70:71]
	s_nop 0
	v_pk_add_f32 v[66:67], v[66:67], v[68:69]
	s_nop 0
	v_add_f32_e32 v65, v66, v67
	v_mov_b32_e32 v66, v65
	s_nop 1
	v_permlane16_swap_b32_e32 v66, v65
	v_add_f32_e32 v65, v65, v66
	v_mov_b32_e32 v66, v65
	s_nop 1
	v_permlane32_swap_b32_e32 v66, v65
	v_add_f32_e32 v65, v65, v66
	v_fmamk_f32 v65, v65, 0x3c800000, v178
	v_mul_f32_e32 v66, 0x4b800000, v65
	v_cmp_gt_f32_e32 vcc, s81, v65
	s_nop 1
	v_cndmask_b32_e32 v65, v65, v66, vcc
	v_rsq_f32_e32 v65, v65
	s_nop 0
	v_mul_f32_e32 v66, 0x45800000, v65
	v_cndmask_b32_e32 v68, v65, v66, vcc
.LBB0_137:
	v_lshlrev_b64 v[66:67], 12, v[164:165]
	v_pk_mul_f32 v[60:61], v[60:61], v[68:69] op_sel_hi:[1,0]
	v_lshl_add_u64 v[66:67], v[166:167], 0, v[66:67]
	v_pk_mul_f32 v[60:61], v[150:151], v[60:61]
	v_pk_mul_f32 v[58:59], v[58:59], v[68:69] op_sel_hi:[1,0]
	v_pk_mul_f32 v[56:57], v[56:57], v[68:69] op_sel_hi:[1,0]
	v_pk_mul_f32 v[62:63], v[62:63], v[68:69] op_sel_hi:[1,0]
	v_pk_mul_f32 v[72:73], v[156:157], v[58:59]
	v_pk_mul_f32 v[58:59], v[148:149], v[56:57]
	v_cvt_pk_bf16_f32 v56, v60, v61
	v_add_co_u32_e32 v60, vcc, s83, v66
	v_pk_mul_f32 v[62:63], v[152:153], v[62:63]
	s_nop 0
	v_addc_co_u32_e32 v61, vcc, 0, v67, vcc
	v_cvt_pk_bf16_f32 v57, v62, v63
	v_pk_mul_f32 v[50:51], v[50:51], v[68:69] op_sel_hi:[1,0]
	v_pk_mul_f32 v[48:49], v[48:49], v[68:69] op_sel_hi:[1,0]
	v_lshl_add_u64 v[70:71], v[66:67], 0, s[24:25]
	v_cvt_pk_bf16_f32 v58, v58, v59
	v_cvt_pk_bf16_f32 v59, v72, v73
	global_store_dwordx4 v[60:61], v[56:59], off nt
	v_pk_mul_f32 v[54:55], v[54:55], v[68:69] op_sel_hi:[1,0]
	v_pk_mul_f32 v[52:53], v[52:53], v[68:69] op_sel_hi:[1,0]
	v_pk_mul_f32 v[56:57], v[162:163], v[50:51]
	v_pk_mul_f32 v[50:51], v[154:155], v[48:49]
	s_and_b64 vcc, exec, s[6:7]
	v_pk_mul_f32 v[54:55], v[160:161], v[54:55]
	v_pk_mul_f32 v[52:53], v[158:159], v[52:53]
	s_nop 0
	v_cvt_pk_bf16_f32 v48, v52, v53
	v_cvt_pk_bf16_f32 v49, v54, v55
	v_cvt_pk_bf16_f32 v50, v50, v51
	v_cvt_pk_bf16_f32 v51, v56, v57
	global_store_dwordx4 v[70:71], v[48:51], off offset:64 nt
	s_cbranch_vccnz .LBB0_139
	s_nop 0
	v_pk_mul_f32 v[48:49], v[46:47], v[46:47]
	v_pk_mul_f32 v[50:51], v[44:45], v[44:45]
	s_nop 0
	v_pk_mov_b32 v[52:53], v[50:51], v[48:49] op_sel:[1,0]
	v_mov_b32_e32 v51, v49
	v_pk_add_f32 v[48:49], v[52:53], v[50:51]
	v_pk_mul_f32 v[50:51], v[42:43], v[42:43]
	v_pk_mul_f32 v[52:53], v[40:41], v[40:41]
	v_pk_add_f32 v[48:49], v[48:49], v[48:49] op_sel:[0,1] op_sel_hi:[1,0]
	v_pk_mov_b32 v[54:55], v[52:53], v[50:51] op_sel:[1,0]
	v_mov_b32_e32 v53, v51
	v_pk_add_f32 v[50:51], v[54:55], v[52:53]
	v_mul_f32_e32 v52, v32, v32
	v_mul_f32_e32 v53, v33, v33
	v_pk_add_f32 v[50:51], v[50:51], v[50:51] op_sel:[0,1] op_sel_hi:[1,0]
	v_mov_b32_e32 v49, v52
	v_mov_b32_e32 v51, v53
	v_pk_add_f32 v[48:49], v[48:49], v[50:51]
	v_mul_f32_e32 v50, v37, v37
	v_mul_f32_e32 v52, v39, v39
	v_mul_f32_e32 v54, v34, v34
	v_mul_f32_e32 v55, v35, v35
	v_pk_fma_f32 v[50:51], v[36:37], v[36:37], v[50:51] op_sel_hi:[1,1,0]
	v_pk_fma_f32 v[52:53], v[38:39], v[38:39], v[52:53] op_sel_hi:[1,1,0]
	v_mov_b32_e32 v51, v54
	v_mov_b32_e32 v53, v55
	v_pk_add_f32 v[50:51], v[50:51], v[52:53]
	s_nop 0
	v_pk_add_f32 v[48:49], v[48:49], v[50:51]
	s_nop 0
	v_add_f32_e32 v48, v48, v49
	v_mov_b32_e32 v49, v48
	s_nop 1
	v_permlane16_swap_b32_e32 v49, v48
	v_add_f32_e32 v48, v48, v49
	v_mov_b32_e32 v49, v48
	s_nop 1
	v_permlane32_swap_b32_e32 v49, v48
	v_add_f32_e32 v48, v48, v49
	v_fmamk_f32 v48, v48, 0x3c800000, v178
	v_mul_f32_e32 v49, 0x4b800000, v48
	v_cmp_gt_f32_e32 vcc, s81, v48
	s_nop 1
	v_cndmask_b32_e32 v48, v48, v49, vcc
	v_rsq_f32_e32 v48, v48
	s_nop 0
	v_mul_f32_e32 v49, 0x45800000, v48
	v_cndmask_b32_e32 v64, v48, v49, vcc
; __device__ __forceinline__ u32x4 pack8(const f32x4& a, const f32x4& b) { u32x4 w; w.x = pk2(a[0], a[1]); w.y = pk2(a[2], a[3]); w.z = pk2(b[0], b[1]); w.w = pk2(b[2], b[3]); return w; }
;     __device__ __forceinline__ void operator()(const AccT& acc, const Unit& u, int wr, int wc, int fr, int fq) const {
;     ...
;                 const int row = row0 + ai * 128 + m * 16; float rs = 1.f;
;                 if (kind < 2) { float ss = 0.f;
; #pragma unroll
;                     for (int bj = 0; bj < 2; ++bj)
; #pragma unroll
;                         for (int n = 0; n < 2; ++n) { const f32x4 v = acc[ai][bj][m][n]; ss += (v[0] * v[0] + v[1] * v[1]) + (v[2] * v[2] + v[3] * v[3]); }
;                     ss += __shfl_xor(ss, 16); ss += __shfl_xor(ss, 32); rs = rsqrtf(ss * (1.f / 64.f) + EPS); }
;                 bf16_t* rp = base + (size_t)row * BR + tile * 256 + 64 * wc + 8 * fq;
; #pragma unroll
;                 for (int bj = 0; bj < 2; ++bj) { const f32x4 v0 = acc[ai][bj][m][0] * rs * gv[bj][0], v1 = acc[ai][bj][m][1] * rs * gv[bj][1];
;                     __builtin_nontemporal_store(pack8(v0, v1), (u32x4*)(rp + 32 * bj)); }
.LBB0_139:
	v_pk_mul_f32 v[44:45], v[44:45], v[64:65] op_sel_hi:[1,0]
	v_pk_mul_f32 v[42:43], v[42:43], v[64:65] op_sel_hi:[1,0]
	v_pk_mul_f32 v[44:45], v[150:151], v[44:45]
	v_pk_mul_f32 v[40:41], v[40:41], v[64:65] op_sel_hi:[1,0]
	v_pk_mul_f32 v[46:47], v[46:47], v[64:65] op_sel_hi:[1,0]
	v_pk_mul_f32 v[50:51], v[156:157], v[42:43]
	v_pk_mul_f32 v[42:43], v[148:149], v[40:41]
	v_cvt_pk_bf16_f32 v40, v44, v45
	v_add_co_u32_e32 v44, vcc, s84, v66
	v_pk_mul_f32 v[46:47], v[152:153], v[46:47]
	s_nop 0
	v_addc_co_u32_e32 v45, vcc, 0, v67, vcc
	v_cvt_pk_bf16_f32 v41, v46, v47
	v_pk_mul_f32 v[36:37], v[36:37], v[64:65] op_sel_hi:[1,0]
	v_pk_mul_f32 v[34:35], v[34:35], v[64:65] op_sel_hi:[1,0]
	v_pk_mul_f32 v[32:33], v[32:33], v[64:65] op_sel_hi:[1,0]
	v_lshl_add_u64 v[48:49], v[66:67], 0, s[36:37]
	v_cvt_pk_bf16_f32 v42, v42, v43
	v_cvt_pk_bf16_f32 v43, v50, v51
	global_store_dwordx4 v[44:45], v[40:43], off nt
	v_pk_mul_f32 v[38:39], v[38:39], v[64:65] op_sel_hi:[1,0]
	v_pk_mul_f32 v[36:37], v[158:159], v[36:37]
	v_pk_mul_f32 v[40:41], v[162:163], v[34:35]
	v_pk_mul_f32 v[34:35], v[154:155], v[32:33]
	v_cvt_pk_bf16_f32 v32, v36, v37
	v_pk_mul_f32 v[38:39], v[160:161], v[38:39]
	s_and_b64 vcc, exec, s[6:7]
	v_cvt_pk_bf16_f32 v33, v38, v39
	v_cvt_pk_bf16_f32 v34, v34, v35
	v_cvt_pk_bf16_f32 v35, v40, v41
	global_store_dwordx4 v[48:49], v[32:35], off offset:64 nt
	v_mov_b32_e32 v36, 1.0
	s_nop 0
	v_mov_b32_e32 v32, 1.0
	s_cbranch_vccnz .LBB0_141
	v_pk_mul_f32 v[34:35], v[30:31], v[30:31]
	v_pk_mul_f32 v[36:37], v[28:29], v[28:29]
	v_mul_f32_e32 v33, v16, v16
	v_pk_mov_b32 v[38:39], v[36:37], v[34:35] op_sel:[1,0]
	v_mov_b32_e32 v37, v35
	v_pk_add_f32 v[34:35], v[38:39], v[36:37]
	v_pk_mul_f32 v[36:37], v[26:27], v[26:27]
	v_pk_mul_f32 v[38:39], v[24:25], v[24:25]
	v_pk_add_f32 v[34:35], v[34:35], v[34:35] op_sel:[0,1] op_sel_hi:[1,0]
	v_pk_mov_b32 v[40:41], v[38:39], v[36:37] op_sel:[1,0]
	v_mov_b32_e32 v39, v37
	v_pk_add_f32 v[36:37], v[40:41], v[38:39]
	v_mul_f32_e32 v38, v17, v17
	v_pk_add_f32 v[36:37], v[36:37], v[36:37] op_sel:[0,1] op_sel_hi:[1,0]
	v_mov_b32_e32 v35, v33
	v_mov_b32_e32 v37, v38
	v_pk_add_f32 v[34:35], v[34:35], v[36:37]
	v_mul_f32_e32 v36, v21, v21
	v_mul_f32_e32 v39, v18, v18
	v_pk_fma_f32 v[36:37], v[20:21], v[20:21], v[36:37] op_sel_hi:[1,1,0]
	v_mul_f32_e32 v38, v23, v23
	v_mul_f32_e32 v40, v19, v19
	v_mov_b32_e32 v37, v39
	v_pk_fma_f32 v[38:39], v[22:23], v[22:23], v[38:39] op_sel_hi:[1,1,0]
	s_nop 0
	v_mov_b32_e32 v39, v40
	v_pk_add_f32 v[36:37], v[36:37], v[38:39]
	s_nop 0
	v_pk_add_f32 v[34:35], v[34:35], v[36:37]
	s_nop 0
	v_add_f32_e32 v33, v34, v35
	v_mov_b32_e32 v34, v33
	s_nop 1
	v_permlane16_swap_b32_e32 v34, v33
	v_add_f32_e32 v33, v33, v34
	v_mov_b32_e32 v34, v33
	s_nop 1
	v_permlane32_swap_b32_e32 v34, v33
	v_add_f32_e32 v33, v33, v34
	v_fmamk_f32 v33, v33, 0x3c800000, v178
	v_mul_f32_e32 v34, 0x4b800000, v33
	v_cmp_gt_f32_e32 vcc, s81, v33
	s_nop 1
	v_cndmask_b32_e32 v33, v33, v34, vcc
	v_rsq_f32_e32 v33, v33
	s_nop 0
	v_mul_f32_e32 v34, 0x45800000, v33
	v_cndmask_b32_e32 v36, v33, v34, vcc
.LBB0_141:
	v_lshlrev_b64 v[34:35], 12, v[164:165]
	v_pk_mul_f32 v[28:29], v[28:29], v[36:37] op_sel_hi:[1,0]
	v_lshl_add_u64 v[34:35], v[166:167], 0, v[34:35]
	v_pk_mul_f32 v[28:29], v[150:151], v[28:29]
	v_pk_mul_f32 v[26:27], v[26:27], v[36:37] op_sel_hi:[1,0]
	v_pk_mul_f32 v[24:25], v[24:25], v[36:37] op_sel_hi:[1,0]
	v_pk_mul_f32 v[30:31], v[30:31], v[36:37] op_sel_hi:[1,0]
	v_pk_mul_f32 v[40:41], v[156:157], v[26:27]
	v_pk_mul_f32 v[26:27], v[148:149], v[24:25]
	v_cvt_pk_bf16_f32 v24, v28, v29
	v_add_co_u32_e32 v28, vcc, s85, v34
	v_pk_mul_f32 v[30:31], v[152:153], v[30:31]
	s_nop 0
	v_addc_co_u32_e32 v29, vcc, 0, v35, vcc
	v_cvt_pk_bf16_f32 v25, v30, v31
	v_pk_mul_f32 v[18:19], v[18:19], v[36:37] op_sel_hi:[1,0]
	v_pk_mul_f32 v[16:17], v[16:17], v[36:37] op_sel_hi:[1,0]
	v_lshl_add_u64 v[38:39], v[34:35], 0, s[38:39]
	v_cvt_pk_bf16_f32 v26, v26, v27
	v_cvt_pk_bf16_f32 v27, v40, v41
	global_store_dwordx4 v[28:29], v[24:27], off nt
	v_pk_mul_f32 v[22:23], v[22:23], v[36:37] op_sel_hi:[1,0]
	v_pk_mul_f32 v[20:21], v[20:21], v[36:37] op_sel_hi:[1,0]
	v_pk_mul_f32 v[24:25], v[162:163], v[18:19]
	v_pk_mul_f32 v[18:19], v[154:155], v[16:17]
	s_and_b64 vcc, exec, s[6:7]
	v_pk_mul_f32 v[22:23], v[160:161], v[22:23]
	v_pk_mul_f32 v[20:21], v[158:159], v[20:21]
	s_nop 0
	v_cvt_pk_bf16_f32 v16, v20, v21
	v_cvt_pk_bf16_f32 v17, v22, v23
	v_cvt_pk_bf16_f32 v18, v18, v19
	v_cvt_pk_bf16_f32 v19, v24, v25
	global_store_dwordx4 v[38:39], v[16:19], off offset:64 nt
	s_cbranch_vccnz .LBB0_143
	s_nop 0
	v_pk_mul_f32 v[16:17], v[14:15], v[14:15]
	v_pk_mul_f32 v[18:19], v[12:13], v[12:13]
	s_nop 0
	v_pk_mov_b32 v[20:21], v[18:19], v[16:17] op_sel:[1,0]
	v_mov_b32_e32 v19, v17
	v_pk_add_f32 v[16:17], v[20:21], v[18:19]
	v_pk_mul_f32 v[18:19], v[10:11], v[10:11]
	v_pk_mul_f32 v[20:21], v[8:9], v[8:9]
	v_pk_add_f32 v[16:17], v[16:17], v[16:17] op_sel:[0,1] op_sel_hi:[1,0]
	v_pk_mov_b32 v[22:23], v[20:21], v[18:19] op_sel:[1,0]
	v_mov_b32_e32 v21, v19
	v_pk_add_f32 v[18:19], v[22:23], v[20:21]
	v_mul_f32_e32 v20, v0, v0
	v_mul_f32_e32 v21, v1, v1
	v_pk_add_f32 v[18:19], v[18:19], v[18:19] op_sel:[0,1] op_sel_hi:[1,0]
	v_mov_b32_e32 v17, v20
	v_mov_b32_e32 v19, v21
	v_pk_add_f32 v[16:17], v[16:17], v[18:19]
	v_mul_f32_e32 v18, v5, v5
	v_mul_f32_e32 v20, v7, v7
	v_mul_f32_e32 v22, v2, v2
	v_mul_f32_e32 v23, v3, v3
	v_pk_fma_f32 v[18:19], v[4:5], v[4:5], v[18:19] op_sel_hi:[1,1,0]
	v_pk_fma_f32 v[20:21], v[6:7], v[6:7], v[20:21] op_sel_hi:[1,1,0]
	v_mov_b32_e32 v19, v22
	v_mov_b32_e32 v21, v23
	v_pk_add_f32 v[18:19], v[18:19], v[20:21]
	s_nop 0
	v_pk_add_f32 v[16:17], v[16:17], v[18:19]
	s_nop 0
	v_add_f32_e32 v16, v16, v17
	v_mov_b32_e32 v17, v16
	s_nop 1
	v_permlane16_swap_b32_e32 v17, v16
	v_add_f32_e32 v16, v16, v17
	v_mov_b32_e32 v17, v16
	s_nop 1
	v_permlane32_swap_b32_e32 v17, v16
	v_add_f32_e32 v16, v16, v17
	v_fmamk_f32 v16, v16, 0x3c800000, v178
	v_mul_f32_e32 v17, 0x4b800000, v16
	v_cmp_gt_f32_e32 vcc, s81, v16
	s_nop 1
	v_cndmask_b32_e32 v16, v16, v17, vcc
	v_rsq_f32_e32 v16, v16
	s_nop 0
	v_mul_f32_e32 v17, 0x45800000, v16
	v_cndmask_b32_e32 v32, v16, v17, vcc
